# split-phase barrier around P7 in local mode: seam 6 arrives cross-XCD without waiting or L2 write-back, the wait for that generation moves to seam 7
# speedup vs baseline: 1.0196x; 1.0056x over previous
.LBB0_809:
	s_andn2_saveexec_b64 s[8:9], s[8:9]
	s_cbranch_execz .LBB0_827
	s_mov_b64 s[8:9], exec
	v_readlane_b32 s3, v255, 0
	s_cmp_eq_u32 s3, 0
	s_cbranch_scc1 .Lnowb6
	buffer_wbl2 sc1
.Lnowb6:
	s_waitcnt lgkmcnt(0)
	s_waitcnt vmcnt(0)
	v_mbcnt_lo_u32_b32 v1, s8, 0
	v_mbcnt_hi_u32_b32 v1, s9, v1
	v_cmp_eq_u32_e32 vcc, 0, v1
	s_and_saveexec_b64 s[10:11], vcc
	s_cbranch_execz .LBB0_812
	s_bcnt1_i32_b64 s3, s[8:9]
	v_mov_b32_e32 v2, 0x1e03000
	v_mov_b32_e32 v3, s3
	global_atomic_add v2, v2, v3, s[78:79] offset:1024 sc0
.LBB0_812:
	s_or_b64 exec, exec, s[10:11]
	v_cvt_f32_u32_e32 v3, v0
	s_waitcnt vmcnt(0)
	v_readfirstlane_b32 s3, v2
	s_add_u32 s10, s78, 0x1e03500
	s_addc_u32 s11, s79, 0
	v_rcp_iflag_f32_e32 v3, v3
	v_add_u32_e32 v1, s3, v1
	v_add_u32_e32 v4, 1, v1
	s_mov_b64 s[12:13], -1
	v_mul_f32_e32 v2, 0x4f7ffffe, v3
	v_cvt_u32_f32_e32 v2, v2
	v_sub_u32_e32 v3, 0, v0
	v_mul_lo_u32 v3, v3, v2
	v_mul_hi_u32 v3, v2, v3
	v_add_u32_e32 v2, v2, v3
	v_mul_hi_u32 v2, v1, v2
	v_mul_lo_u32 v3, v2, v0
	v_sub_u32_e32 v1, v1, v3
	v_add_u32_e32 v5, 1, v2
	v_cmp_ge_u32_e32 vcc, v1, v0
	v_sub_u32_e32 v3, v1, v0
	s_nop 0
	v_cndmask_b32_e32 v2, v2, v5, vcc
	v_cndmask_b32_e32 v1, v1, v3, vcc
	v_add_u32_e32 v3, 1, v2
	v_cmp_ge_u32_e32 vcc, v1, v0
	s_nop 1
	v_cndmask_b32_e32 v2, v2, v3, vcc
	v_mul_lo_u32 v1, v0, v2
	v_add_u32_e32 v0, v1, v0
	v_cmp_ne_u32_e32 vcc, v4, v0
	v_mov_b64_e32 v[0:1], s[10:11]
	s_and_saveexec_b64 s[8:9], vcc
	s_cbranch_execz .LBB0_824
	v_readlane_b32 s3, v255, 0
	s_cmp_eq_u32 s3, 0
	s_cbranch_scc1 .LBB0_826
	v_mov_b32_e32 v0, 0
	global_load_dword v1, v0, s[10:11] sc1
	s_mov_b64 s[16:17], 0
	s_waitcnt vmcnt(0)
	v_cmp_eq_u32_e32 vcc, v1, v2
	s_and_saveexec_b64 s[14:15], vcc
	s_cbranch_execz .LBB0_823
	s_add_u32 s12, s78, 0x1e00200
	s_addc_u32 s13, s79, 0
	s_mov_b32 s3, 1
	s_branch .LBB0_816

.Lloc_s7:
	s_add_u32 s10, s78, 0x1e03500
	s_addc_u32 s11, s79, 0
	v_mov_b32_e32 v0, 0
.Lw7:
	global_load_dword v1, v0, s[10:11] sc1
	s_waitcnt vmcnt(0)
	v_readfirstlane_b32 s3, v1
	s_cmp_ge_u32 s3, 4
	s_cbranch_scc1 .Lw7done
	s_sleep 1
	s_branch .Lw7
